# RWKV scan step: ka/kb and va/vb broadcast operands materialised as (x,x) register pairs, packed ops no longer use op_sel broadcast
# baseline (speedup 1.0000x reference)
; __device__ __forceinline__ void phase_rwkv(KP P, int l_, unsigned char* shm) {
;     ...
;                 const float* cf = sCoef + (c & 1) * CS; const float* vb = sV + (c % 3) * T * 64; float* ob = sO + (c & 1) * T * 64;
;     ...
;                 f32x4 Aw0, Aw1, Akk0, Akk1, Ab0, Ab1, Ak0, Ak1, Ar0, Ar1; float Ava, Avb;
;                 f32x4 Bw0, Bw1, Bkk0, Bkk1, Bb0, Bb1, Bk0, Bk1, Br0, Br1; float Bva, Bvb;
;                 RW_LD(A, 0);
.LBB0_2515:
	s_and_b32 s1, s42, 1
	s_waitcnt vmcnt(26)
	v_cndmask_b32_e64 v0, 0, 1, s[78:79]
	s_mov_b32 s0, 0xa000
	s_mul_i32 s1, s1, 0xa000
	s_mul_i32 s43, s42, 0xab
	v_lshl_or_b32 v253, v0, 13, v173
	v_mul_lo_u32 v0, v0, s0
	s_bfe_u32 s43, s43, 0x70009
	s_waitcnt vmcnt(17)
	v_add_u32_e32 v14, s1, v156
	v_or_b32_e32 v235, v174, v0
	s_mul_i32 s43, s43, 3
	s_waitcnt vmcnt(12)
	ds_read_b128 v[10:13], v14
	ds_read_b128 v[0:3], v14 offset:16
	s_waitcnt vmcnt(0)
	ds_read_b128 v[38:41], v14 offset:8192
	ds_read_b128 v[34:37], v14 offset:8208
	ds_read_b128 v[26:29], v14 offset:16384
	ds_read_b128 v[6:9], v14 offset:16400
	ds_read_b128 v[30:33], v14 offset:24576
	ds_read_b128 v[22:25], v14 offset:24592
	s_sub_i32 s43, s42, s43
	s_and_b32 s43, s43, 0xff
	s_lshl_b32 s43, s43, 13
	s_add_i32 s43, s43, 0
	v_lshl_add_u32 v4, v123, 2, s43
	v_add_u32_e32 v4, 0x14000, v4
	s_mul_hi_u32 s0, s42, 0xaaaaaaab
	ds_read2_b32 v[106:107], v4
	ds_read2_b32 v[158:159], v4 offset0:32 offset1:32
	ds_read_b128 v[18:21], v14 offset:32768
	ds_read_b128 v[14:17], v14 offset:32784
	s_lshr_b32 s0, s0, 1
	s_mulk_i32 s0, 0xa000
	s_add_i32 s43, s0, 0
	s_mov_b32 s52, -2
	v_mov_b32_e32 v252, v175
	s_waitcnt lgkmcnt(2)
	s_branch .LBB0_2517

; __device__ __forceinline__ void phase_rwkv(KP P, int l_, unsigned char* shm) {
;     ...
;                 f32x4 Aw0, Aw1, Akk0, Akk1, Ab0, Ab1, Ak0, Ak1, Ar0, Ar1; float Ava, Avb;
;                 f32x4 Bw0, Bw1, Bkk0, Bkk1, Bb0, Bb1, Bk0, Bk1, Br0, Br1; float Bva, Bvb;
;                 RW_LD(A, 0);
; #pragma unroll 2
;                 for (int tl = 0; tl < T; tl += 2) {
;                     RW_LD(B, tl + 1);
;                     RW_STEP(A, tl);
;                     RW_LD(A, tl + 2);
;                     RW_STEP(B, tl + 1);
;                 }
.LBB0_2517:
	v_pk_mul_f32 v[110:111], v[40:41], v[92:93]
	v_pk_mul_f32 v[40:41], v[40:41], v[100:101]
	v_pk_fma_f32 v[110:111], v[38:39], v[90:91], v[110:111]
	v_pk_fma_f32 v[38:39], v[38:39], v[98:99], v[40:41]
	v_pk_mul_f32 v[40:41], v[36:37], v[96:97]
	v_pk_mul_f32 v[36:37], v[36:37], v[104:105]
	v_pk_fma_f32 v[40:41], v[34:35], v[94:95], v[40:41]
	v_pk_fma_f32 v[34:35], v[34:35], v[102:103], v[36:37]
	v_pk_add_f32 v[36:37], v[40:41], v[110:111]
	v_pk_add_f32 v[34:35], v[34:35], v[38:39]
	v_add_f32_e32 v36, v36, v37
	v_add_f32_e32 v34, v34, v35
	v_add_u32_e32 v240, 0, v235
	v_add_f32_dpp v35, v36, v36 quad_perm:[1,0,3,2] row_mask:0xf bank_mask:0xf bound_ctrl:1
	v_add_f32_dpp v34, v34, v34 quad_perm:[1,0,3,2] row_mask:0xf bank_mask:0xf bound_ctrl:1
	ds_read_b128 v[62:65], v240
	ds_read_b128 v[50:53], v240 offset:16
	ds_read_b128 v[78:81], v240 offset:8192
	ds_read_b128 v[74:77], v240 offset:8208
	ds_read_b128 v[66:69], v240 offset:16384
	ds_read_b128 v[54:57], v240 offset:16400
	ds_read_b128 v[70:73], v240 offset:24576
	ds_read_b128 v[58:61], v240 offset:24592
	ds_read_b128 v[46:49], v240 offset:32768
	ds_read_b128 v[42:45], v240 offset:32784
	v_add_f32_dpp v35, v35, v35 quad_perm:[2,3,0,1] row_mask:0xf bank_mask:0xf bound_ctrl:1
	v_add_f32_dpp v36, v34, v34 quad_perm:[2,3,0,1] row_mask:0xf bank_mask:0xf bound_ctrl:1
	v_add_u32_e32 v186, s43, v252
	v_add_f32_dpp v34, v35, v35 row_half_mirror row_mask:0xf bank_mask:0xf bound_ctrl:1
	v_add_f32_dpp v36, v36, v36 row_half_mirror row_mask:0xf bank_mask:0xf bound_ctrl:1
	v_mov_b32_e32 v35, v34
	v_mov_b32_e32 v37, v36
	v_pk_mul_f32 v[38:39], v[26:27], v[34:35] neg_lo:[0,1] neg_hi:[0,1]
	v_pk_mul_f32 v[26:27], v[26:27], v[36:37] neg_lo:[0,1] neg_hi:[0,1]
	v_pk_fma_f32 v[38:39], v[10:11], v[90:91], v[38:39]
	v_pk_fma_f32 v[10:11], v[10:11], v[98:99], v[26:27]
	s_waitcnt lgkmcnt(13)
	v_pk_fma_f32 v[110:111], v[30:31], v[106:107], v[38:39]
	v_pk_fma_f32 v[98:99], v[30:31], v[158:159], v[10:11]
	v_pk_mul_f32 v[10:11], v[28:29], v[34:35] neg_lo:[0,1] neg_hi:[0,1]
	ds_read2_b32 v[108:109], v186
	ds_read2_b32 v[160:161], v186 offset0:32 offset1:32
	v_pk_fma_f32 v[10:11], v[12:13], v[92:93], v[10:11]
	v_add_u32_e32 v187, 0, v253
	v_pk_fma_f32 v[92:93], v[32:33], v[106:107], v[10:11]
	v_pk_mul_f32 v[10:11], v[28:29], v[36:37] neg_lo:[0,1] neg_hi:[0,1]
	s_nop 0
	v_pk_fma_f32 v[10:11], v[12:13], v[100:101], v[10:11]
	s_nop 0
	v_pk_fma_f32 v[100:101], v[32:33], v[158:159], v[10:11]
	v_pk_mul_f32 v[10:11], v[6:7], v[34:35] neg_lo:[0,1] neg_hi:[0,1]
	v_pk_mul_f32 v[6:7], v[6:7], v[36:37] neg_lo:[0,1] neg_hi:[0,1]
	v_pk_fma_f32 v[10:11], v[0:1], v[94:95], v[10:11]
	v_pk_fma_f32 v[0:1], v[0:1], v[102:103], v[6:7]
	s_waitcnt lgkmcnt(14)
	v_pk_fma_f32 v[94:95], v[22:23], v[106:107], v[10:11]
	v_pk_fma_f32 v[102:103], v[22:23], v[158:159], v[0:1]
	v_pk_mul_f32 v[0:1], v[8:9], v[34:35] neg_lo:[0,1] neg_hi:[0,1]
	s_nop 0
	v_pk_fma_f32 v[0:1], v[2:3], v[96:97], v[0:1]
	s_nop 0
	v_pk_fma_f32 v[96:97], v[24:25], v[106:107], v[0:1]
	v_pk_mul_f32 v[0:1], v[8:9], v[36:37] neg_lo:[0,1] neg_hi:[0,1]
	s_waitcnt lgkmcnt(12)
	v_pk_mul_f32 v[6:7], v[16:17], v[96:97]
	v_pk_fma_f32 v[0:1], v[2:3], v[104:105], v[0:1]
	v_pk_mul_f32 v[2:3], v[20:21], v[100:101]
	v_pk_fma_f32 v[104:105], v[24:25], v[158:159], v[0:1]
	v_pk_mul_f32 v[0:1], v[20:21], v[92:93]
	v_pk_mul_f32 v[8:9], v[16:17], v[104:105]
	v_pk_fma_f32 v[0:1], v[18:19], v[110:111], v[0:1]
	v_pk_fma_f32 v[2:3], v[18:19], v[98:99], v[2:3]
	v_pk_fma_f32 v[6:7], v[14:15], v[94:95], v[6:7]
	v_pk_fma_f32 v[8:9], v[14:15], v[102:103], v[8:9]
	v_pk_add_f32 v[0:1], v[0:1], v[6:7]
	v_pk_add_f32 v[2:3], v[2:3], v[8:9]
	v_add_f32_e32 v0, v0, v1
	v_add_f32_e32 v1, v2, v3
	s_nop 0
	v_add_f32_dpp v0, v0, v0 quad_perm:[1,0,3,2] row_mask:0xf bank_mask:0xf bound_ctrl:1
	v_add_f32_dpp v1, v1, v1 quad_perm:[1,0,3,2] row_mask:0xf bank_mask:0xf bound_ctrl:1
	s_nop 0
	v_add_f32_dpp v0, v0, v0 quad_perm:[2,3,0,1] row_mask:0xf bank_mask:0xf bound_ctrl:1
	v_add_f32_dpp v1, v1, v1 quad_perm:[2,3,0,1] row_mask:0xf bank_mask:0xf bound_ctrl:1
	s_nop 0
	v_mov_b32_dpp v2, v0 row_half_mirror row_mask:0xf bank_mask:0xf bound_ctrl:1
	v_mov_b32_dpp v3, v1 row_half_mirror row_mask:0xf bank_mask:0xf bound_ctrl:1
	s_and_saveexec_b64 s[72:73], s[6:7]
	s_cbranch_execz .LBB0_2519
	v_add_f32_e32 v0, v0, v2
	v_add_u32_e32 v2, 0x1e000, v187
	v_add_f32_e32 v1, v1, v3
	v_add_u32_e32 v3, 0x1e080, v187
	ds_write_b32 v2, v0
	ds_write_b32 v3, v1
; __device__ __forceinline__ void phase_rwkv(KP P, int l_, unsigned char* shm) {
;     ...
;                 f32x4 Aw0, Aw1, Akk0, Akk1, Ab0, Ab1, Ak0, Ak1, Ar0, Ar1; float Ava, Avb;
;                 f32x4 Bw0, Bw1, Bkk0, Bkk1, Bb0, Bb1, Bk0, Bk1, Br0, Br1; float Bva, Bvb;
;                 RW_LD(A, 0);
; #pragma unroll 2
;                 for (int tl = 0; tl < T; tl += 2) {
;                     RW_LD(B, tl + 1);
;                     RW_STEP(A, tl);
;                     RW_LD(A, tl + 2);
;                     RW_STEP(B, tl + 1);
;                 }
.LBB0_2519:
	s_or_b64 exec, exec, s[72:73]
	s_waitcnt lgkmcnt(9)
	v_pk_mul_f32 v[106:107], v[80:81], v[92:93]
	v_pk_mul_f32 v[80:81], v[80:81], v[100:101]
	v_pk_fma_f32 v[106:107], v[78:79], v[110:111], v[106:107]
	v_pk_fma_f32 v[78:79], v[78:79], v[98:99], v[80:81]
	s_waitcnt lgkmcnt(8)
	v_pk_mul_f32 v[80:81], v[76:77], v[96:97]
	v_pk_mul_f32 v[76:77], v[76:77], v[104:105]
	v_pk_fma_f32 v[80:81], v[74:75], v[94:95], v[80:81]
	v_pk_fma_f32 v[74:75], v[74:75], v[102:103], v[76:77]
	v_pk_add_f32 v[76:77], v[106:107], v[80:81]
	v_pk_add_f32 v[74:75], v[78:79], v[74:75]
	v_add_f32_e32 v4, v76, v77
	v_add_f32_e32 v74, v74, v75
	s_waitcnt lgkmcnt(0)
	v_add_f32_dpp v4, v4, v4 quad_perm:[1,0,3,2] row_mask:0xf bank_mask:0xf bound_ctrl:1
	v_add_f32_dpp v74, v74, v74 quad_perm:[1,0,3,2] row_mask:0xf bank_mask:0xf bound_ctrl:1
	ds_read_b128 v[22:25], v240 offset:256
	ds_read_b128 v[10:13], v240 offset:272
	ds_read_b128 v[38:41], v240 offset:8448
	ds_read_b128 v[34:37], v240 offset:8464
	ds_read_b128 v[26:29], v240 offset:16640
	ds_read_b128 v[14:17], v240 offset:16656
	ds_read_b128 v[30:33], v240 offset:24832
	ds_read_b128 v[18:21], v240 offset:24848
	ds_read_b128 v[6:9], v240 offset:33024
	ds_read_b128 v[0:3], v240 offset:33040
	ds_read2_b32 v[90:91], v186 offset0:64 offset1:64
	ds_read2_b32 v[162:163], v186 offset0:96 offset1:96
	v_add_f32_dpp v4, v4, v4 quad_perm:[2,3,0,1] row_mask:0xf bank_mask:0xf bound_ctrl:1
	v_add_f32_dpp v74, v74, v74 quad_perm:[2,3,0,1] row_mask:0xf bank_mask:0xf bound_ctrl:1
	s_nop 0
	v_add_f32_dpp v166, v4, v4 row_half_mirror row_mask:0xf bank_mask:0xf bound_ctrl:1
	v_add_f32_dpp v74, v74, v74 row_half_mirror row_mask:0xf bank_mask:0xf bound_ctrl:1
	v_mov_b32_e32 v167, v166
	v_mov_b32_e32 v75, v74
	v_pk_mul_f32 v[78:79], v[66:67], v[166:167] neg_lo:[0,1] neg_hi:[0,1]
	v_pk_mul_f32 v[66:67], v[66:67], v[74:75] neg_lo:[0,1] neg_hi:[0,1]
	v_pk_fma_f32 v[78:79], v[62:63], v[110:111], v[78:79]
	v_pk_fma_f32 v[62:63], v[62:63], v[98:99], v[66:67]
	v_pk_fma_f32 v[106:107], v[70:71], v[108:109], v[78:79]
	v_pk_fma_f32 v[98:99], v[70:71], v[160:161], v[62:63]
	v_pk_mul_f32 v[62:63], v[68:69], v[166:167] neg_lo:[0,1] neg_hi:[0,1]
	s_nop 0
	v_pk_fma_f32 v[62:63], v[64:65], v[92:93], v[62:63]
	s_nop 0
	v_pk_fma_f32 v[110:111], v[72:73], v[108:109], v[62:63]
	v_pk_mul_f32 v[62:63], v[68:69], v[74:75] neg_lo:[0,1] neg_hi:[0,1]
	s_nop 0
	v_pk_fma_f32 v[62:63], v[64:65], v[100:101], v[62:63]
	s_nop 0
	v_pk_fma_f32 v[112:113], v[72:73], v[160:161], v[62:63]
	v_pk_mul_f32 v[62:63], v[54:55], v[166:167] neg_lo:[0,1] neg_hi:[0,1]
	v_pk_mul_f32 v[54:55], v[54:55], v[74:75] neg_lo:[0,1] neg_hi:[0,1]
	v_pk_fma_f32 v[62:63], v[50:51], v[94:95], v[62:63]
	v_pk_fma_f32 v[50:51], v[50:51], v[102:103], v[54:55]
	v_pk_fma_f32 v[114:115], v[58:59], v[108:109], v[62:63]
	v_pk_fma_f32 v[116:117], v[58:59], v[160:161], v[50:51]
	v_pk_mul_f32 v[50:51], v[56:57], v[166:167] neg_lo:[0,1] neg_hi:[0,1]
	s_nop 0
	v_pk_fma_f32 v[50:51], v[52:53], v[96:97], v[50:51]
	s_nop 0
	v_pk_fma_f32 v[118:119], v[60:61], v[108:109], v[50:51]
	v_pk_mul_f32 v[50:51], v[56:57], v[74:75] neg_lo:[0,1] neg_hi:[0,1]
	s_nop 0
	v_pk_fma_f32 v[50:51], v[52:53], v[104:105], v[50:51]
	s_nop 0
	v_pk_fma_f32 v[120:121], v[60:61], v[160:161], v[50:51]
	v_pk_mul_f32 v[50:51], v[48:49], v[110:111]
	v_pk_mul_f32 v[48:49], v[48:49], v[112:113]
	v_pk_fma_f32 v[50:51], v[46:47], v[106:107], v[50:51]
	v_pk_fma_f32 v[46:47], v[46:47], v[98:99], v[48:49]
	v_pk_mul_f32 v[48:49], v[44:45], v[118:119]
	v_pk_mul_f32 v[44:45], v[44:45], v[120:121]
	v_pk_fma_f32 v[48:49], v[42:43], v[114:115], v[48:49]
	v_pk_fma_f32 v[42:43], v[42:43], v[116:117], v[44:45]
	v_pk_add_f32 v[44:45], v[50:51], v[48:49]
	v_pk_add_f32 v[42:43], v[46:47], v[42:43]
	v_add_f32_e32 v4, v44, v45
	v_add_f32_e32 v42, v42, v43
	s_nop 0
	v_add_f32_dpp v4, v4, v4 quad_perm:[1,0,3,2] row_mask:0xf bank_mask:0xf bound_ctrl:1
	v_add_f32_dpp v42, v42, v42 quad_perm:[1,0,3,2] row_mask:0xf bank_mask:0xf bound_ctrl:1
	s_nop 0
	v_add_f32_dpp v4, v4, v4 quad_perm:[2,3,0,1] row_mask:0xf bank_mask:0xf bound_ctrl:1
	v_add_f32_dpp v42, v42, v42 quad_perm:[2,3,0,1] row_mask:0xf bank_mask:0xf bound_ctrl:1
	s_nop 0
	v_mov_b32_dpp v43, v4 row_half_mirror row_mask:0xf bank_mask:0xf bound_ctrl:1
	v_mov_b32_dpp v44, v42 row_half_mirror row_mask:0xf bank_mask:0xf bound_ctrl:1
	s_and_saveexec_b64 s[72:73], s[6:7]
	s_cbranch_execz .LBB0_2521
	v_add_f32_e32 v4, v4, v43
	v_add_u32_e32 v43, 0x1e100, v187
	v_add_f32_e32 v42, v42, v44
	v_add_u32_e32 v44, 0x1e180, v187
	ds_write_b32 v43, v4
	ds_write_b32 v44, v42
; __device__ __forceinline__ void phase_rwkv(KP P, int l_, unsigned char* shm) {
;     ...
;                 f32x4 Aw0, Aw1, Akk0, Akk1, Ab0, Ab1, Ak0, Ak1, Ar0, Ar1; float Ava, Avb;
;                 f32x4 Bw0, Bw1, Bkk0, Bkk1, Bb0, Bb1, Bk0, Bk1, Br0, Br1; float Bva, Bvb;
;                 RW_LD(A, 0);
; #pragma unroll 2
;                 for (int tl = 0; tl < T; tl += 2) {
;                     RW_LD(B, tl + 1);
;                     RW_STEP(A, tl);
;                     RW_LD(A, tl + 2);
;                     RW_STEP(B, tl + 1);
;                 }
.LBB0_2521:
	s_or_b64 exec, exec, s[72:73]
	s_waitcnt lgkmcnt(9)
	v_pk_mul_f32 v[92:93], v[40:41], v[110:111]
	v_pk_mul_f32 v[40:41], v[40:41], v[112:113]
	v_pk_fma_f32 v[92:93], v[38:39], v[106:107], v[92:93]
	v_pk_fma_f32 v[38:39], v[38:39], v[98:99], v[40:41]
	s_waitcnt lgkmcnt(8)
	v_pk_mul_f32 v[40:41], v[36:37], v[118:119]
	v_pk_mul_f32 v[36:37], v[36:37], v[120:121]
	v_pk_fma_f32 v[40:41], v[34:35], v[114:115], v[40:41]
	v_pk_fma_f32 v[34:35], v[34:35], v[116:117], v[36:37]
	v_pk_add_f32 v[36:37], v[40:41], v[92:93]
	v_pk_add_f32 v[34:35], v[34:35], v[38:39]
	v_add_f32_e32 v4, v36, v37
	v_add_f32_e32 v34, v34, v35
	s_waitcnt lgkmcnt(0)
	v_add_f32_dpp v4, v4, v4 quad_perm:[1,0,3,2] row_mask:0xf bank_mask:0xf bound_ctrl:1
	v_add_f32_dpp v34, v34, v34 quad_perm:[1,0,3,2] row_mask:0xf bank_mask:0xf bound_ctrl:1
	ds_read_b128 v[62:65], v240 offset:512
	ds_read_b128 v[50:53], v240 offset:528
	ds_read_b128 v[78:81], v240 offset:8704
	ds_read_b128 v[74:77], v240 offset:8720
	ds_read_b128 v[66:69], v240 offset:16896
	ds_read_b128 v[54:57], v240 offset:16912
	ds_read_b128 v[70:73], v240 offset:25088
	ds_read_b128 v[58:61], v240 offset:25104
	ds_read_b128 v[46:49], v240 offset:33280
	ds_read_b128 v[42:45], v240 offset:33296
	ds_read2_b32 v[96:97], v186 offset0:128 offset1:128
	ds_read2_b32 v[164:165], v186 offset0:160 offset1:160
	v_add_f32_dpp v4, v4, v4 quad_perm:[2,3,0,1] row_mask:0xf bank_mask:0xf bound_ctrl:1
	v_add_f32_dpp v34, v34, v34 quad_perm:[2,3,0,1] row_mask:0xf bank_mask:0xf bound_ctrl:1
	s_nop 0
	v_add_f32_dpp v168, v4, v4 row_half_mirror row_mask:0xf bank_mask:0xf bound_ctrl:1
	v_add_f32_dpp v34, v34, v34 row_half_mirror row_mask:0xf bank_mask:0xf bound_ctrl:1
	v_mov_b32_e32 v169, v168
	v_mov_b32_e32 v35, v34
	v_pk_mul_f32 v[38:39], v[26:27], v[168:169] neg_lo:[0,1] neg_hi:[0,1]
	v_pk_mul_f32 v[26:27], v[26:27], v[34:35] neg_lo:[0,1] neg_hi:[0,1]
	v_pk_fma_f32 v[38:39], v[22:23], v[106:107], v[38:39]
	v_pk_fma_f32 v[22:23], v[22:23], v[98:99], v[26:27]
	v_pk_fma_f32 v[92:93], v[30:31], v[90:91], v[38:39]
	v_pk_fma_f32 v[94:95], v[30:31], v[162:163], v[22:23]
	v_pk_mul_f32 v[22:23], v[28:29], v[168:169] neg_lo:[0,1] neg_hi:[0,1]
	s_nop 0
	v_pk_fma_f32 v[22:23], v[24:25], v[110:111], v[22:23]
	s_nop 0
	v_pk_fma_f32 v[100:101], v[32:33], v[90:91], v[22:23]
	v_pk_mul_f32 v[22:23], v[28:29], v[34:35] neg_lo:[0,1] neg_hi:[0,1]
	s_nop 0
	v_pk_fma_f32 v[22:23], v[24:25], v[112:113], v[22:23]
	s_nop 0
	v_pk_fma_f32 v[102:103], v[32:33], v[162:163], v[22:23]
	v_pk_mul_f32 v[22:23], v[14:15], v[168:169] neg_lo:[0,1] neg_hi:[0,1]
	v_pk_mul_f32 v[14:15], v[14:15], v[34:35] neg_lo:[0,1] neg_hi:[0,1]
	v_pk_fma_f32 v[22:23], v[10:11], v[114:115], v[22:23]
	v_pk_fma_f32 v[10:11], v[10:11], v[116:117], v[14:15]
	v_pk_fma_f32 v[104:105], v[18:19], v[90:91], v[22:23]
	v_pk_fma_f32 v[108:109], v[18:19], v[162:163], v[10:11]
	v_pk_mul_f32 v[10:11], v[16:17], v[168:169] neg_lo:[0,1] neg_hi:[0,1]
	s_nop 0
	v_pk_fma_f32 v[10:11], v[12:13], v[118:119], v[10:11]
	s_nop 0
	v_pk_fma_f32 v[110:111], v[20:21], v[90:91], v[10:11]
	v_pk_mul_f32 v[10:11], v[16:17], v[34:35] neg_lo:[0,1] neg_hi:[0,1]
	s_nop 0
	v_pk_fma_f32 v[10:11], v[12:13], v[120:121], v[10:11]
	s_nop 0
	v_pk_fma_f32 v[112:113], v[20:21], v[162:163], v[10:11]
	v_pk_mul_f32 v[10:11], v[8:9], v[100:101]
	v_pk_mul_f32 v[8:9], v[8:9], v[102:103]
	v_pk_fma_f32 v[10:11], v[6:7], v[92:93], v[10:11]
	v_pk_fma_f32 v[6:7], v[6:7], v[94:95], v[8:9]
	v_pk_mul_f32 v[8:9], v[2:3], v[110:111]
	v_pk_mul_f32 v[2:3], v[2:3], v[112:113]
	v_pk_fma_f32 v[8:9], v[0:1], v[104:105], v[8:9]
	v_pk_fma_f32 v[0:1], v[0:1], v[108:109], v[2:3]
	v_pk_add_f32 v[2:3], v[10:11], v[8:9]
	v_pk_add_f32 v[0:1], v[6:7], v[0:1]
	v_add_f32_e32 v2, v2, v3
	v_add_f32_e32 v0, v0, v1
	s_nop 0
	v_add_f32_dpp v1, v2, v2 quad_perm:[1,0,3,2] row_mask:0xf bank_mask:0xf bound_ctrl:1
	v_add_f32_dpp v2, v0, v0 quad_perm:[1,0,3,2] row_mask:0xf bank_mask:0xf bound_ctrl:1
	s_nop 0
	v_add_f32_dpp v0, v1, v1 quad_perm:[2,3,0,1] row_mask:0xf bank_mask:0xf bound_ctrl:1
	v_add_f32_dpp v1, v2, v2 quad_perm:[2,3,0,1] row_mask:0xf bank_mask:0xf bound_ctrl:1
	s_nop 0
	v_mov_b32_dpp v2, v0 row_half_mirror row_mask:0xf bank_mask:0xf bound_ctrl:1
	v_mov_b32_dpp v3, v1 row_half_mirror row_mask:0xf bank_mask:0xf bound_ctrl:1
	s_and_saveexec_b64 s[72:73], s[6:7]
	s_cbranch_execz .LBB0_2523
	v_add_f32_e32 v0, v0, v2
	v_add_u32_e32 v2, 0x1e200, v187
	v_add_f32_e32 v1, v1, v3
	v_add_u32_e32 v3, 0x1e280, v187
	ds_write_b32 v2, v0
	ds_write_b32 v3, v1
; __device__ __forceinline__ void phase_rwkv(KP P, int l_, unsigned char* shm) {
;     ...
;                 f32x4 Aw0, Aw1, Akk0, Akk1, Ab0, Ab1, Ak0, Ak1, Ar0, Ar1; float Ava, Avb;
;                 f32x4 Bw0, Bw1, Bkk0, Bkk1, Bb0, Bb1, Bk0, Bk1, Br0, Br1; float Bva, Bvb;
;                 RW_LD(A, 0);
; #pragma unroll 2
;                 for (int tl = 0; tl < T; tl += 2) {
;                     RW_LD(B, tl + 1);
;                     RW_STEP(A, tl);
;                     RW_LD(A, tl + 2);
;                     RW_STEP(B, tl + 1);
;                 }
.LBB0_2523:
	s_or_b64 exec, exec, s[72:73]
	s_waitcnt lgkmcnt(9)
	v_pk_mul_f32 v[90:91], v[80:81], v[100:101]
	v_pk_mul_f32 v[80:81], v[80:81], v[102:103]
	v_pk_fma_f32 v[90:91], v[78:79], v[92:93], v[90:91]
	v_pk_fma_f32 v[78:79], v[78:79], v[94:95], v[80:81]
	s_waitcnt lgkmcnt(8)
	v_pk_mul_f32 v[80:81], v[76:77], v[110:111]
	v_pk_mul_f32 v[76:77], v[76:77], v[112:113]
	v_pk_fma_f32 v[80:81], v[74:75], v[104:105], v[80:81]
	v_pk_fma_f32 v[74:75], v[74:75], v[108:109], v[76:77]
	v_pk_add_f32 v[76:77], v[90:91], v[80:81]
	v_pk_add_f32 v[74:75], v[78:79], v[74:75]
	v_add_f32_e32 v76, v76, v77
	v_add_f32_e32 v74, v74, v75
	s_waitcnt lgkmcnt(0)
	v_add_f32_dpp v75, v76, v76 quad_perm:[1,0,3,2] row_mask:0xf bank_mask:0xf bound_ctrl:1
	v_add_f32_dpp v74, v74, v74 quad_perm:[1,0,3,2] row_mask:0xf bank_mask:0xf bound_ctrl:1
	ds_read_b128 v[10:13], v240 offset:768
	ds_read_b128 v[0:3], v240 offset:784
	ds_read_b128 v[38:41], v240 offset:8960
	ds_read_b128 v[34:37], v240 offset:8976
	ds_read_b128 v[26:29], v240 offset:17152
	ds_read_b128 v[6:9], v240 offset:17168
	ds_read2_b32 v[106:107], v186 offset0:192 offset1:192
	ds_read2_b32 v[158:159], v186 offset0:224 offset1:224
	ds_read_b128 v[30:33], v240 offset:25344
	ds_read_b128 v[22:25], v240 offset:25360
	ds_read_b128 v[18:21], v240 offset:33536
	ds_read_b128 v[14:17], v240 offset:33552
	v_add_f32_dpp v75, v75, v75 quad_perm:[2,3,0,1] row_mask:0xf bank_mask:0xf bound_ctrl:1
	v_add_f32_dpp v76, v74, v74 quad_perm:[2,3,0,1] row_mask:0xf bank_mask:0xf bound_ctrl:1
	s_waitcnt lgkmcnt(4)
	v_add_f32_dpp v74, v75, v75 row_half_mirror row_mask:0xf bank_mask:0xf bound_ctrl:1
	v_add_f32_dpp v76, v76, v76 row_half_mirror row_mask:0xf bank_mask:0xf bound_ctrl:1
	v_mov_b32_e32 v75, v74
	v_mov_b32_e32 v77, v76
	v_pk_mul_f32 v[80:81], v[66:67], v[74:75] neg_lo:[0,1] neg_hi:[0,1]
	v_pk_mul_f32 v[66:67], v[66:67], v[76:77] neg_lo:[0,1] neg_hi:[0,1]
	v_pk_fma_f32 v[80:81], v[62:63], v[92:93], v[80:81]
	v_pk_fma_f32 v[62:63], v[62:63], v[94:95], v[66:67]
	v_pk_fma_f32 v[90:91], v[70:71], v[96:97], v[80:81]
	v_pk_fma_f32 v[98:99], v[70:71], v[164:165], v[62:63]
	v_pk_mul_f32 v[62:63], v[68:69], v[74:75] neg_lo:[0,1] neg_hi:[0,1]
	s_nop 0
	v_pk_fma_f32 v[62:63], v[64:65], v[100:101], v[62:63]
	s_nop 0
	v_pk_fma_f32 v[92:93], v[72:73], v[96:97], v[62:63]
	v_pk_mul_f32 v[62:63], v[68:69], v[76:77] neg_lo:[0,1] neg_hi:[0,1]
	s_nop 0
	v_pk_fma_f32 v[62:63], v[64:65], v[102:103], v[62:63]
	s_nop 0
	v_pk_fma_f32 v[100:101], v[72:73], v[164:165], v[62:63]
	v_pk_mul_f32 v[62:63], v[54:55], v[74:75] neg_lo:[0,1] neg_hi:[0,1]
	v_pk_mul_f32 v[54:55], v[54:55], v[76:77] neg_lo:[0,1] neg_hi:[0,1]
	v_pk_fma_f32 v[62:63], v[50:51], v[104:105], v[62:63]
	v_pk_fma_f32 v[50:51], v[50:51], v[108:109], v[54:55]
	v_pk_fma_f32 v[94:95], v[58:59], v[96:97], v[62:63]
	v_pk_fma_f32 v[102:103], v[58:59], v[164:165], v[50:51]
	v_pk_mul_f32 v[50:51], v[56:57], v[74:75] neg_lo:[0,1] neg_hi:[0,1]
	s_nop 0
	v_pk_fma_f32 v[50:51], v[52:53], v[110:111], v[50:51]
	s_nop 0
	v_pk_fma_f32 v[96:97], v[60:61], v[96:97], v[50:51]
	v_pk_mul_f32 v[50:51], v[56:57], v[76:77] neg_lo:[0,1] neg_hi:[0,1]
	s_nop 0
	v_pk_fma_f32 v[50:51], v[52:53], v[112:113], v[50:51]
	s_nop 0
	v_pk_fma_f32 v[104:105], v[60:61], v[164:165], v[50:51]
	v_pk_mul_f32 v[50:51], v[48:49], v[92:93]
	v_pk_mul_f32 v[48:49], v[48:49], v[100:101]
	v_pk_fma_f32 v[50:51], v[46:47], v[90:91], v[50:51]
	v_pk_fma_f32 v[46:47], v[46:47], v[98:99], v[48:49]
	v_pk_mul_f32 v[48:49], v[44:45], v[96:97]
	v_pk_mul_f32 v[44:45], v[44:45], v[104:105]
	v_pk_fma_f32 v[48:49], v[42:43], v[94:95], v[48:49]
	v_pk_fma_f32 v[42:43], v[42:43], v[102:103], v[44:45]
	v_pk_add_f32 v[44:45], v[50:51], v[48:49]
	v_pk_add_f32 v[42:43], v[46:47], v[42:43]
	v_add_f32_e32 v44, v44, v45
	v_add_f32_e32 v42, v42, v43
	s_nop 0
	v_add_f32_dpp v43, v44, v44 quad_perm:[1,0,3,2] row_mask:0xf bank_mask:0xf bound_ctrl:1
	v_add_f32_dpp v44, v42, v42 quad_perm:[1,0,3,2] row_mask:0xf bank_mask:0xf bound_ctrl:1
	s_nop 0
	v_add_f32_dpp v42, v43, v43 quad_perm:[2,3,0,1] row_mask:0xf bank_mask:0xf bound_ctrl:1
	v_add_f32_dpp v43, v44, v44 quad_perm:[2,3,0,1] row_mask:0xf bank_mask:0xf bound_ctrl:1
	s_nop 0
	v_mov_b32_dpp v44, v42 row_half_mirror row_mask:0xf bank_mask:0xf bound_ctrl:1
	v_mov_b32_dpp v45, v43 row_half_mirror row_mask:0xf bank_mask:0xf bound_ctrl:1
	s_and_saveexec_b64 s[72:73], s[6:7]
	s_cbranch_execz .LBB0_2516
	v_add_f32_e32 v42, v42, v44
	v_add_u32_e32 v44, 0x1e300, v187
	v_add_f32_e32 v43, v43, v45
	v_add_u32_e32 v45, 0x1e380, v187
	ds_write_b32 v44, v42
	ds_write_b32 v45, v43
	s_branch .LBB0_2516
